# scan phase: staging waits counted by wave role (output-tile stores / table-row loads stay in flight) on top of the chunk de-serialisation
# speedup vs baseline: 1.0057x; 1.0057x over previous
; #define LAS __attribute__((address_space(3)))
; DI void phase_scan(int l, int wv, bool fill, bool last) {
;     ...
;         for (int c = 0; c < 36; ++c) {
;             const int row0 = chunk_row0(c);
;             __syncthreads();
;             *(LAS u32x4*)(L + O_QT + srow * RS + sc16 * 2) = q0; *(LAS u32x4*)(L + O_QT + srow * RS + sc16 * 2 + 16) = q1;
;             *(LAS u32x4*)(L + O_KT + srow * RS + sc16 * 2) = k0; *(LAS u32x4*)(L + O_KT + srow * RS + sc16 * 2 + 16) = k1;
;             *(LAS u32x4*)(L + O_V + srow * RS64 + svc * 2) = vr;
;             if (tid < 96) *(LAS f32x4*)(L + O_EV + tid * 16) = evr;
.LBB0_484:
	s_barrier
	s_cmp_eq_u32 s78, 0
	s_cbranch_scc1 .Lscan_wait_drain
	s_and_b64 vcc, exec, s[56:57]
	s_cbranch_vccnz .Lscan_wait_fill
	s_and_b64 vcc, exec, s[58:59]
	s_cbranch_vccz .Lscan_wait_drain
	s_cmp_gt_u32 s78, 4
	s_cbranch_scc1 .Lscan_wait_out
	v_readlane_b32 s62, v254, 33
	s_nop 3
	s_cmp_eq_u32 s62, 0
	s_cbranch_scc1 .Lscan_wait_drain
.Lscan_wait_out:
	s_waitcnt vmcnt(19)
	ds_write_b128 v197, v[72:75]
	ds_write_b128 v197, v[64:67] offset:16
	s_waitcnt vmcnt(17)
	ds_write_b128 v197, v[80:83] offset:17408
	ds_write_b128 v197, v[76:79] offset:17424
	s_waitcnt vmcnt(16)
	ds_write_b128 v198, v[84:87] offset:52224
	s_branch .Lscan_wait_done
.Lscan_wait_fill:
	s_cmp_gt_u32 s78, 31
	s_cbranch_scc1 .Lscan_wait_drain
	s_waitcnt vmcnt(14)
	ds_write_b128 v197, v[72:75]
	ds_write_b128 v197, v[64:67] offset:16
	s_waitcnt vmcnt(12)
	ds_write_b128 v197, v[80:83] offset:17408
	ds_write_b128 v197, v[76:79] offset:17424
	s_waitcnt vmcnt(11)
	ds_write_b128 v198, v[84:87] offset:52224
	s_branch .Lscan_wait_done
.Lscan_wait_drain:
	s_waitcnt vmcnt(3)
	ds_write_b128 v197, v[72:75]
	ds_write_b128 v197, v[64:67] offset:16
	s_waitcnt vmcnt(1)
	ds_write_b128 v197, v[80:83] offset:17408
	ds_write_b128 v197, v[76:79] offset:17424
	s_waitcnt vmcnt(0)
	ds_write_b128 v198, v[84:87] offset:52224
.Lscan_wait_done:
	s_and_saveexec_b64 s[60:61], s[36:37]
	ds_write_b128 v199, v[68:71]
	s_or_b64 exec, exec, s[60:61]
	s_add_i32 s80, s78, 1
	s_cmp_eq_u32 s78, 35
	s_cbranch_scc1 .LBB0_494
	s_cmp_gt_u32 s78, 2
	s_mov_b64 s[60:61], -1
	s_cbranch_scc0 .LBB0_489
	s_sub_i32 s62, 34, s78
	s_add_i32 s63, s78, -3
	s_and_b64 s[60:61], s[10:11], exec
	s_cselect_b32 s62, s63, s62
	s_mov_b64 s[60:61], 0

; DI void phase_scan(int l, int wv, bool fill, bool last) {
;     ...
;             __syncthreads();
;             if (filler && c < 32) {
;                 const int it = fidx + 1024 * c, e = it >> 1; unsigned char* dst = (it & 1) ? (unsigned char*)F.V : (unsigned char*)F.U;
;                 float am = 0.f;
; #pragma unroll
;                 for (int c8 = 0; c8 < 8; ++c8) am = fmaxf(am, fmaxf(fmaxf(fabsf(fx[c8].x), fabsf(fx[c8].y)), fmaxf(fabsf(fx[c8].z), fabsf(fx[c8].w))));
; #pragma unroll
;                 for (int o = 1; o < 64; o <<= 1) am = fmaxf(am, __shfl_xor(am, o));
;                 const float inv = am > 0.f ? 7.0f / am : 0.f, sc = am > 0.f ? am * (1.0f / 7.0f) : 0.f;
;                 v32h hx;
; #pragma unroll
;                 for (int c8 = 0; c8 < 8; ++c8) { hx[c8 * 4 + 0] = (_Float16)(fx[c8].x * inv); hx[c8 * 4 + 1] = (_Float16)(fx[c8].y * inv); hx[c8 * 4 + 2] = (_Float16)(fx[c8].z * inv); hx[c8 * 4 + 3] = (_Float16)(fx[c8].w * inv); }
;                 const v6i p = __builtin_amdgcn_cvt_scalef32_pk32_fp6_f16(hx, 1.0f);
;                 eseg_store(dst, e, lane, p);
;                 if (lane == 0) ((float*)(F.ws + WS_ESCALE) + ((it & 1) ? NEXP : 0))[e] = sc;
.LBB0_498:
	s_cmp_lt_u32 s78, 32
	s_cselect_b64 s[62:63], -1, 0
	s_and_b64 s[62:63], s[56:57], s[62:63]
	s_andn2_b64 vcc, exec, s[62:63]
	s_waitcnt lgkmcnt(0)
	s_barrier
	s_cbranch_vccnz .LBB0_503
	s_waitcnt vmcnt(5)
	v_max_f32_e64 v16, |v35|, |v35|
	v_max_f32_e64 v17, |v34|, |v34|
	v_max_f32_e32 v16, v17, v16
	v_max_f32_e64 v17, |v43|, |v43|
	v_max_f32_e64 v18, |v42|, |v42|
	v_max_f32_e32 v17, v18, v17
	v_max3_f32 v16, |v32|, |v33|, v16
	v_max3_f32 v17, |v40|, |v41|, v17
	v_max3_f32 v16, v16, 0, v17
	v_max_f32_e64 v17, |v55|, |v55|
	v_max_f32_e64 v18, |v54|, |v54|
	v_max_f32_e32 v17, v18, v17
	v_max_f32_e64 v18, |v63|, |v63|
	v_max_f32_e64 v19, |v62|, |v62|
	v_max_f32_e32 v18, v19, v18
	v_max3_f32 v17, |v52|, |v53|, v17
	v_max3_f32 v18, |v60|, |v61|, v18
	v_max3_f32 v16, v16, v17, v18
	v_max_f32_e64 v17, |v51|, |v51|
	v_max_f32_e64 v18, |v50|, |v50|
	v_max_f32_e32 v17, v18, v17
	v_max_f32_e64 v18, |v39|, |v39|
	v_max_f32_e64 v19, |v38|, |v38|
	v_max_f32_e32 v18, v19, v18
	v_max3_f32 v17, |v48|, |v49|, v17
	v_max3_f32 v18, |v36|, |v37|, v18
	v_max3_f32 v16, v16, v17, v18
	v_max_f32_e64 v17, |v47|, |v47|
	v_max_f32_e64 v18, |v46|, |v46|
	v_max_f32_e32 v17, v18, v17
	v_max_f32_e64 v18, |v59|, |v59|
	v_max_f32_e64 v19, |v58|, |v58|
	v_max_f32_e32 v18, v19, v18
	v_max3_f32 v17, |v44|, |v45|, v17
	v_max3_f32 v18, |v56|, |v57|, v18
	v_max3_f32 v16, v16, v17, v18
	s_mov_b32 s64, 0x40e00000
	s_lshl_b32 s81, s78, 10
	s_add_i32 s81, s81, s67
	s_nop 1
	v_max_f32_dpp v16, v16, v16 quad_perm:[1,0,3,2] row_mask:0xf bank_mask:0xf bound_ctrl:1
	s_nop 1
	v_max_f32_dpp v16, v16, v16 quad_perm:[2,3,0,1] row_mask:0xf bank_mask:0xf bound_ctrl:1
	s_nop 1
	v_max_f32_dpp v16, v16, v16 row_half_mirror row_mask:0xf bank_mask:0xf bound_ctrl:1
	s_nop 1
	v_max_f32_dpp v16, v16, v16 row_mirror row_mask:0xf bank_mask:0xf bound_ctrl:1
	v_mov_b32_e32 v17, v16
	s_nop 1
	v_permlane16_swap_b32_e32 v16, v17
	s_nop 1
	v_max_f32_e32 v16, v16, v17
	v_mov_b32_e32 v17, v16
	s_nop 1
	v_permlane32_swap_b32_e32 v16, v17
	s_nop 1
	v_max_f32_e32 v159, v16, v17
	v_div_scale_f32 v16, s[62:63], v159, v159, s64
	v_rcp_f32_e32 v17, v16
	s_ashr_i32 s62, s81, 1
	v_fma_f32 v18, -v16, v17, 1.0
	v_fmac_f32_e32 v17, v18, v17
	v_div_scale_f32 v18, vcc, s64, v159, s64
	v_mul_f32_e32 v19, v18, v17
	v_fma_f32 v20, -v16, v19, v18
	v_fmac_f32_e32 v19, v20, v17
	v_fma_f32 v16, -v16, v19, v18
	v_div_fmas_f32 v16, v16, v17, v19
	v_div_fixup_f32 v16, v16, v159, s64
	v_cmp_lt_f32_e32 vcc, 0, v159
	v_mov_b32_e32 v17, v34
	s_nop 0
	v_cndmask_b32_e32 v208, 0, v16, vcc
	v_mov_b32_e32 v16, v33
	v_pk_mul_f32 v[16:17], v[16:17], v[208:209] op_sel_hi:[1,0]
	v_fma_mixlo_f16 v18, v32, v208, 0
	v_cvt_pk_f16_f32 v17, v16, v17
	v_pack_b32_f16 v16, v18, v17
	v_pk_mov_b32 v[18:19], v[34:35], v[40:41] op_sel:[1,0]
	s_nop 0
	v_pk_mul_f32 v[18:19], v[18:19], v[208:209] op_sel_hi:[1,0]
	s_nop 0
	v_cvt_pk_f16_f32 v20, v18, v19
	v_mov_b32_e32 v18, v41
	v_mov_b32_e32 v19, v42
	v_pk_mul_f32 v[18:19], v[18:19], v[208:209] op_sel_hi:[1,0]
	v_alignbit_b32 v17, v20, v17, 16
	v_cvt_pk_f16_f32 v19, v18, v19
	v_alignbit_b32 v18, v19, v20, 16
	v_pk_mov_b32 v[20:21], v[42:43], v[52:53] op_sel:[1,0]
	s_nop 0
	v_pk_mul_f32 v[20:21], v[20:21], v[208:209] op_sel_hi:[1,0]
	s_nop 0
	v_cvt_pk_f16_f32 v22, v20, v21
	v_mov_b32_e32 v20, v53
	v_mov_b32_e32 v21, v54
	v_pk_mul_f32 v[20:21], v[20:21], v[208:209] op_sel_hi:[1,0]
	v_alignbit_b32 v19, v22, v19, 16
	v_cvt_pk_f16_f32 v21, v20, v21
	v_alignbit_b32 v20, v21, v22, 16
	v_pk_mov_b32 v[22:23], v[54:55], v[60:61] op_sel:[1,0]
	s_nop 0
	v_pk_mul_f32 v[22:23], v[22:23], v[208:209] op_sel_hi:[1,0]
	s_nop 0
	v_cvt_pk_f16_f32 v24, v22, v23
	v_mov_b32_e32 v22, v61
	v_mov_b32_e32 v23, v62
	v_pk_mul_f32 v[22:23], v[22:23], v[208:209] op_sel_hi:[1,0]
	v_alignbit_b32 v21, v24, v21, 16
	v_cvt_pk_f16_f32 v23, v22, v23
	v_alignbit_b32 v22, v23, v24, 16
	v_pk_mov_b32 v[24:25], v[62:63], v[48:49] op_sel:[1,0]
	s_nop 0
	v_pk_mul_f32 v[24:25], v[24:25], v[208:209] op_sel_hi:[1,0]
	s_nop 0
	v_cvt_pk_f16_f32 v26, v24, v25
	v_mov_b32_e32 v24, v49
	v_mov_b32_e32 v25, v50
	v_pk_mul_f32 v[24:25], v[24:25], v[208:209] op_sel_hi:[1,0]
	v_alignbit_b32 v23, v26, v23, 16
	v_cvt_pk_f16_f32 v25, v24, v25
	v_alignbit_b32 v24, v25, v26, 16
	v_pk_mov_b32 v[26:27], v[50:51], v[36:37] op_sel:[1,0]
	s_nop 0
	v_pk_mul_f32 v[26:27], v[26:27], v[208:209] op_sel_hi:[1,0]
	s_nop 0
	v_cvt_pk_f16_f32 v28, v26, v27
	v_mov_b32_e32 v26, v37
	v_mov_b32_e32 v27, v38
	v_pk_mul_f32 v[26:27], v[26:27], v[208:209] op_sel_hi:[1,0]
	v_alignbit_b32 v25, v28, v25, 16
	v_cvt_pk_f16_f32 v27, v26, v27
	v_alignbit_b32 v26, v27, v28, 16
	v_pk_mov_b32 v[28:29], v[38:39], v[44:45] op_sel:[1,0]
	s_nop 0
	v_pk_mul_f32 v[28:29], v[28:29], v[208:209] op_sel_hi:[1,0]
	s_nop 0
	v_cvt_pk_f16_f32 v30, v28, v29
	v_mov_b32_e32 v28, v45
	v_mov_b32_e32 v29, v46
	v_pk_mul_f32 v[28:29], v[28:29], v[208:209] op_sel_hi:[1,0]
	v_alignbit_b32 v27, v30, v27, 16
	v_cvt_pk_f16_f32 v29, v28, v29
	v_alignbit_b32 v28, v29, v30, 16
	v_pk_mov_b32 v[30:31], v[46:47], v[56:57] op_sel:[1,0]
	s_nop 0
	v_pk_mul_f32 v[30:31], v[30:31], v[208:209] op_sel_hi:[1,0]
	s_nop 0
	v_cvt_pk_f16_f32 v161, v30, v31
	v_mov_b32_e32 v30, v57
	v_mov_b32_e32 v31, v58
	v_pk_mul_f32 v[30:31], v[30:31], v[208:209] op_sel_hi:[1,0]
	v_alignbit_b32 v29, v161, v29, 16
	v_cvt_pk_f16_f32 v31, v30, v31
	v_alignbit_b32 v30, v31, v161, 16
	v_lshrrev_b32_e32 v31, 16, v31
	v_fma_mixhi_f16 v31, v59, v208, 0
	v_cvt_scalef32_pk32_fp6_f16 v[232:237], v[16:31], 1.0
	s_lshl_b32 s64, s62, 7
	s_mov_b32 s65, 0
	v_lshl_add_u64 v[16:17], v[122:123], 0, s[64:65]
	global_store_dwordx4 v[16:17], v[232:235], off
	v_and_b32_e32 v18, 7, v239
	s_lshl_b32 s64, s62, 6
	v_lshlrev_b32_e32 v18, 3, v18
	s_sub_u32 s64, 0x200000, s64
	v_mov_b32_e32 v19, 0
	v_sub_u32_e32 v18, s64, v18
	v_lshl_add_u64 v[18:19], v[16:17], 0, v[18:19]
	global_store_dwordx2 v[18:19], v[236:237], off
	s_and_saveexec_b64 s[64:65], s[40:41]
	s_cbranch_execz .LBB0_501
	s_ashr_i32 s63, s62, 31
	s_lshl_b64 s[62:63], s[62:63], 2
	s_add_u32 s62, s70, s62
	v_mul_f32_e32 v16, 0x3e124925, v159
	s_addc_u32 s63, s71, s63
	v_cndmask_b32_e32 v16, 0, v16, vcc
	global_store_dword v129, v16, s[62:63]
